# stack10 + packed even/odd row sums placed at the end of each PV slot (one slot behind the exps)
# baseline (speedup 1.0000x reference)
.LBB1_525:
	v_lshl_add_u32 v65, s24, 15, v240
	s_waitcnt lgkmcnt(11)
	v_mfma_f32_32x32x16_bf16 v[0:15], v[190:193], v[178:181], v[0:15]
	v_add_u32_e32 v78, v65, v242
	ds_read_b128 v[66:69], v78 offset:16384
	s_nop 4
	v_exp_f32_e32 v80, v80
	v_exp_f32_e32 v81, v81
	s_waitcnt lgkmcnt(11)
	v_mfma_f32_32x32x16_bf16 v[48:63], v[186:189], v[178:181], v[48:63]
	ds_read_b128 v[70:73], v78 offset:20480
	v_exp_f32_e32 v82, v82
	v_exp_f32_e32 v83, v83
	v_mov_b64_e32 v[198:199], v[80:81]
	s_waitcnt lgkmcnt(11)
	v_mfma_f32_32x32x16_bf16 v[32:47], v[182:185], v[178:181], v[32:47]
	ds_read_b128 v[74:77], v78 offset:24576
	v_exp_f32_e32 v84, v84
	v_exp_f32_e32 v85, v85
	v_pk_add_f32 v[198:199], v[198:199], v[82:83]
	s_waitcnt lgkmcnt(11)
	v_mfma_f32_32x32x16_bf16 v[16:31], v[142:145], v[178:181], v[16:31]
	ds_read_b128 v[182:185], v78 offset:28672
	v_exp_f32_e32 v86, v86
	v_exp_f32_e32 v87, v87
	v_pk_add_f32 v[198:199], v[198:199], v[84:85]
	s_waitcnt lgkmcnt(3)
	v_mfma_f32_32x32x16_bf16 v[0:15], v[66:69], v[138:141], v[0:15]
	v_add_u32_e32 v178, v65, v241
	ds_read_b128 v[142:145], v178 offset:16384
	v_exp_f32_e32 v88, v88
	v_exp_f32_e32 v89, v89
	v_pk_add_f32 v[198:199], v[198:199], v[86:87]
	s_waitcnt lgkmcnt(3)
	v_mfma_f32_32x32x16_bf16 v[48:63], v[70:73], v[138:141], v[48:63]
	ds_read_b128 v[66:69], v178 offset:20480
	v_exp_f32_e32 v90, v90
	v_exp_f32_e32 v91, v91
	v_pk_add_f32 v[198:199], v[198:199], v[88:89]
	s_waitcnt lgkmcnt(3)
	v_mfma_f32_32x32x16_bf16 v[32:47], v[74:77], v[138:141], v[32:47]
	ds_read_b128 v[70:73], v178 offset:24576
	v_exp_f32_e32 v92, v92
	v_exp_f32_e32 v93, v93
	v_pk_add_f32 v[198:199], v[198:199], v[90:91]
	s_waitcnt lgkmcnt(3)
	v_mfma_f32_32x32x16_bf16 v[16:31], v[182:185], v[138:141], v[16:31]
	ds_read_b128 v[74:77], v178 offset:28672
	v_exp_f32_e32 v94, v94
	v_exp_f32_e32 v95, v95
	v_pk_add_f32 v[198:199], v[198:199], v[92:93]
	s_waitcnt lgkmcnt(3)
	v_mfma_f32_32x32x16_bf16 v[0:15], v[142:145], v[134:137], v[0:15]
	v_add_u32_e32 v65, v65, v239
	ds_read_b128 v[138:141], v65 offset:16384
	v_exp_f32_e32 v96, v96
	v_exp_f32_e32 v97, v97
	v_pk_add_f32 v[198:199], v[198:199], v[94:95]
	s_waitcnt lgkmcnt(3)
	v_mfma_f32_32x32x16_bf16 v[48:63], v[66:69], v[134:137], v[48:63]
	ds_read_b128 v[142:145], v65 offset:20480
	v_exp_f32_e32 v98, v98
	v_exp_f32_e32 v99, v99
	v_pk_add_f32 v[198:199], v[198:199], v[96:97]
	s_waitcnt lgkmcnt(3)
	v_mfma_f32_32x32x16_bf16 v[32:47], v[70:73], v[134:137], v[32:47]
	ds_read_b128 v[66:69], v65 offset:24576
	v_exp_f32_e32 v100, v100
	v_exp_f32_e32 v101, v101
	v_pk_add_f32 v[198:199], v[198:199], v[98:99]
	s_waitcnt lgkmcnt(3)
	v_mfma_f32_32x32x16_bf16 v[16:31], v[74:77], v[134:137], v[16:31]
	ds_read_b128 v[70:73], v65 offset:28672
	v_exp_f32_e32 v102, v102
	v_exp_f32_e32 v103, v103
	v_pk_add_f32 v[198:199], v[198:199], v[100:101]
	s_waitcnt lgkmcnt(3)
	v_mfma_f32_32x32x16_bf16 v[0:15], v[138:141], v[130:133], v[0:15]
	v_exp_f32_e32 v104, v104
	v_exp_f32_e32 v105, v105
	v_pk_add_f32 v[198:199], v[198:199], v[102:103]
	s_waitcnt lgkmcnt(2)
	v_mfma_f32_32x32x16_bf16 v[48:63], v[142:145], v[130:133], v[48:63]
	v_exp_f32_e32 v106, v106
	v_exp_f32_e32 v107, v107
	v_pk_add_f32 v[198:199], v[198:199], v[104:105]
	s_waitcnt lgkmcnt(1)
	v_mfma_f32_32x32x16_bf16 v[32:47], v[66:69], v[130:133], v[32:47]
	v_exp_f32_e32 v108, v108
	v_exp_f32_e32 v109, v109
	v_pk_add_f32 v[198:199], v[198:199], v[106:107]
	s_waitcnt lgkmcnt(0)
	v_mfma_f32_32x32x16_bf16 v[16:31], v[70:73], v[130:133], v[16:31]
	v_exp_f32_e32 v110, v110
	v_exp_f32_e32 v111, v111
	v_pk_add_f32 v[198:199], v[198:199], v[108:109]
	s_nop 0
	v_pk_add_f32 v[198:199], v[198:199], v[110:111]
	v_add_f32_e32 v66, v198, v199
	v_mov_b32_e32 v65, v66
	v_mov_b32_e32 v67, v66
	s_nop 1
	v_permlane32_swap_b32_e32 v65, v67
	v_add_f32_e32 v65, v65, v67
	v_cmp_ngt_f32_e64 s[38:39], s71, v65
	s_mov_b64 vcc, s[38:39]
	s_cbranch_vccz .LBB1_530
	v_cndmask_b32_e64 v65, 0, 1, s[36:37]
	v_cmp_ne_u32_e32 vcc, 0, v65
	s_cbranch_vccz .LBB1_533
	v_mov_b32_e32 v65, v64
	v_mov_b32_e32 v66, v64
	v_mov_b32_e32 v67, v64
	v_mov_b32_e32 v68, v64
	v_mov_b32_e32 v69, v64
	v_mov_b32_e32 v70, v64
	v_mov_b32_e32 v71, v64
	v_mov_b32_e32 v72, v64
	v_mov_b32_e32 v73, v64
	v_mov_b32_e32 v74, v64
	v_mov_b32_e32 v75, v64
	v_mov_b32_e32 v76, v64
	v_mov_b32_e32 v77, v64
	v_mov_b32_e32 v78, v64
	v_mov_b32_e32 v79, v64
	s_nop 1
	v_mfma_f32_32x32x16_bf16 v[80:95], v[166:169], v[126:129], v[64:79]
	v_mfma_f32_32x32x16_bf16 v[64:79], v[174:177], v[126:129], v[64:79]
	v_mfma_f32_32x32x16_bf16 v[80:95], v[170:173], v[122:125], v[80:95]
	v_mfma_f32_32x32x16_bf16 v[64:79], v[162:165], v[122:125], v[64:79]
	v_mfma_f32_32x32x16_bf16 v[80:95], v[158:161], v[118:121], v[80:95]
	v_mfma_f32_32x32x16_bf16 v[64:79], v[154:157], v[118:121], v[64:79]
	v_mfma_f32_32x32x16_bf16 v[80:95], v[150:153], v[114:117], v[80:95]
	v_mfma_f32_32x32x16_bf16 v[64:79], v[146:149], v[114:117], v[64:79]
	s_cbranch_execnz .LBB1_529
